# v22 + one-time 40x64-cycle stagger of odd wave slots at ffn_in entry (de-phase co-resident blocks)
# speedup vs baseline: 1.0145x; 1.0145x over previous
; #define TIDX tid_()
; DEVI int wave_() { return __builtin_amdgcn_readfirstlane(tid_() >> 6); }
; DEVI bool tile_map(int it, int NTN, int& tm, int& tn) {
;     const int G = gridDim.x;
;     if ((G & 7) != 0) { const int t = blockIdx.x + it * G; if (t >= 128 * NTN) return false; tm = t / NTN; tn = t % NTN; return true; }
;     const int x = blockIdx.x & 7, nb = G >> 3, q = it * nb + (blockIdx.x >> 3);
; DEVI void phase_ffn_in(const Params& p, int l, int which, bf16_t* smem) {
;     unsigned char* ws = p.ws;
;     const bf16_t* A = (const bf16_t*)(ws + OFF_HB);
;     const bf16_t* Bt = (const bf16_t*)(ws + OFF_W + (size_t)l * SZ_LAYER + (which ? OL_W1T1 : OL_W1T0));
;     bf16_t* act = (bf16_t*)(ws + OFF_ACT);
;     const int lane = TIDX & 63, wave = wave_(), wr = wave >> 1, wc = wave & 1, l16 = lane & 15, quad = lane >> 4;
;     int tm, tn;
;     bool have = tile_map(0, 44, tm, tn);
;     if (have) gemm_issue0(A + (size_t)tm * 128 * 1024, 1024, Bt + (size_t)tn * 128 * 1024, 1024, smem);
.LBB0_778:
	s_andn2_b64 vcc, exec, s[0:1]
	s_cbranch_vccnz .LBB0_803
	s_getreg_b32 s0, hwreg(HW_REG_HW_ID, 0, 4)
	s_and_b32 s0, s0, 1
	s_cmp_eq_u32 s0, 0
	s_cbranch_scc1 .Lffn_nosleep
	s_sleep 40
.Lffn_nosleep:
	v_mov_b32_e32 v0, v133
	v_mov_b32_e32 v2, v133
	s_load_dword s4, s[18:19], 0x0
	v_readfirstlane_b32 s26, v2
	s_waitcnt lgkmcnt(0)
	s_and_b32 s6, s4, 7
	s_cmp_lg_u32 s6, 0
	s_cselect_b64 s[0:1], -1, 0
	s_cmp_eq_u32 s6, 0
	s_cbranch_scc1 .LBB0_781
	v_readlane_b32 s24, v222, 16
	s_mov_b64 s[10:11], 0
	v_readlane_b32 s25, v222, 17
	s_branch .LBB0_782
